# mlstm_c: vmcnt(0) guarding the next unit's loads moved from the head to the end of the norm/gate section (wait at the consumer)
# speedup vs baseline: 1.0015x; 1.0015x over previous
.LBB0_611:
	s_or_b64 exec, exec, s[12:13]
	s_waitcnt lgkmcnt(0)
	s_barrier
	ds_read2st64_b32 v[8:9], v140 offset0:4 offset1:6
	s_and_b32 s13, s52, 7
	s_lshl_b32 s12, s52, 4
	s_and_b32 s12, s12, 0xffffff80
	s_lshl_b32 s68, s13, 8
	s_waitcnt lgkmcnt(0)
	v_add_f32_e32 v8, v8, v9
	v_fmamk_f32 v8, v8, 0x3c000000, v184
	v_mul_f32_e32 v9, 0x4b800000, v8
	v_cmp_gt_f32_e32 vcc, s81, v8
	s_mov_b32 s52, s82
	v_cndmask_b32_e32 v8, v8, v9, vcc
	v_add_u32_e32 v9, v141, v165
	ds_read_b64 v[14:15], v9
	v_rsq_f32_e32 v8, v8
	s_waitcnt lgkmcnt(0)
	v_lshlrev_b32_e32 v28, 16, v14
	v_and_b32_e32 v14, 0xffff0000, v14
	v_mul_f32_e32 v28, 0xbfb8aa3b, v28
	v_mul_f32_e32 v14, 0xbfb8aa3b, v14
	v_exp_f32_e32 v28, v28
	v_exp_f32_e32 v29, v14
	v_mul_f32_e32 v9, 0x45800000, v8
	v_cndmask_b32_e32 v8, v8, v9, vcc
	v_lshl_add_u32 v9, s13, 9, v173
	ds_read_b128 v[10:13], v9
	v_lshlrev_b32_e32 v30, 16, v15
	v_and_b32_e32 v31, 0xffff0000, v15
	v_add_f32_e32 v14, 1.0, v28
	v_add_f32_e32 v15, 1.0, v29
	v_rcp_f32_e32 v14, v14
	v_rcp_f32_e32 v15, v15
	v_mul_f32_e32 v30, 0xbfb8aa3b, v30
	v_mul_f32_e32 v31, 0xbfb8aa3b, v31
	v_pk_mul_f32 v[28:29], v[42:43], v[8:9] op_sel_hi:[1,0]
	v_exp_f32_e32 v30, v30
	v_exp_f32_e32 v31, v31
	s_waitcnt lgkmcnt(0)
	v_pk_mul_f32 v[10:11], v[10:11], v[28:29]
	v_pk_mul_f32 v[26:27], v[26:27], v[8:9] op_sel_hi:[1,0]
	v_pk_mul_f32 v[10:11], v[14:15], v[10:11]
	v_pk_mul_f32 v[14:15], v[40:41], v[8:9] op_sel_hi:[1,0]
	v_cvt_pk_bf16_f32 v10, v10, v11
	v_add_u32_e32 v11, v141, v166
	v_add_f32_e32 v28, 1.0, v30
	v_add_f32_e32 v29, 1.0, v31
	v_pk_mul_f32 v[12:13], v[12:13], v[14:15]
	ds_read_b64 v[14:15], v11
	v_rcp_f32_e32 v28, v28
	v_rcp_f32_e32 v29, v29
	v_pk_mul_f32 v[22:23], v[22:23], v[8:9] op_sel_hi:[1,0]
	v_pk_mul_f32 v[18:19], v[18:19], v[8:9] op_sel_hi:[1,0]
	s_waitcnt lgkmcnt(0)
	v_lshlrev_b32_e32 v30, 16, v15
	v_pk_mul_f32 v[12:13], v[28:29], v[12:13]
	v_lshlrev_b32_e32 v28, 16, v14
	v_and_b32_e32 v14, 0xffff0000, v14
	v_mul_f32_e32 v28, 0xbfb8aa3b, v28
	v_mul_f32_e32 v14, 0xbfb8aa3b, v14
	v_exp_f32_e32 v28, v28
	v_exp_f32_e32 v29, v14
	v_cvt_pk_bf16_f32 v11, v12, v13
	v_add_u32_e32 v12, v142, v165
	ds_write_b64 v12, v[10:11] offset:2048
	ds_read_b128 v[10:13], v9 offset:32
	v_and_b32_e32 v31, 0xffff0000, v15
	v_add_f32_e32 v14, 1.0, v28
	v_add_f32_e32 v15, 1.0, v29
	v_rcp_f32_e32 v14, v14
	v_rcp_f32_e32 v15, v15
	v_mul_f32_e32 v30, 0xbfb8aa3b, v30
	v_mul_f32_e32 v31, 0xbfb8aa3b, v31
	v_pk_mul_f32 v[28:29], v[38:39], v[8:9] op_sel_hi:[1,0]
	v_exp_f32_e32 v30, v30
	v_exp_f32_e32 v31, v31
	s_waitcnt lgkmcnt(0)
	v_pk_mul_f32 v[10:11], v[10:11], v[28:29]
	v_pk_mul_f32 v[6:7], v[6:7], v[8:9] op_sel_hi:[1,0]
	v_pk_mul_f32 v[10:11], v[10:11], v[14:15]
	v_pk_mul_f32 v[14:15], v[36:37], v[8:9] op_sel_hi:[1,0]
	v_cvt_pk_bf16_f32 v10, v10, v11
	v_add_u32_e32 v11, v141, v167
	v_add_f32_e32 v28, 1.0, v30
	v_add_f32_e32 v29, 1.0, v31
	v_pk_mul_f32 v[12:13], v[12:13], v[14:15]
	ds_read_b64 v[14:15], v11
	v_rcp_f32_e32 v28, v28
	v_rcp_f32_e32 v29, v29
	v_pk_mul_f32 v[4:5], v[4:5], v[8:9] op_sel_hi:[1,0]
	s_andn2_b64 vcc, exec, s[74:75]
	s_waitcnt lgkmcnt(0)
	v_lshlrev_b32_e32 v30, 16, v15
	v_pk_mul_f32 v[12:13], v[12:13], v[28:29]
	v_lshlrev_b32_e32 v28, 16, v14
	v_and_b32_e32 v14, 0xffff0000, v14
	v_mul_f32_e32 v28, 0xbfb8aa3b, v28
	v_mul_f32_e32 v14, 0xbfb8aa3b, v14
	v_exp_f32_e32 v28, v28
	v_exp_f32_e32 v29, v14
	v_cvt_pk_bf16_f32 v11, v12, v13
	v_add_u32_e32 v12, v142, v166
	ds_write_b64 v12, v[10:11] offset:2048
	ds_read_b128 v[10:13], v9 offset:64
	v_and_b32_e32 v31, 0xffff0000, v15
	v_add_f32_e32 v14, 1.0, v28
	v_add_f32_e32 v15, 1.0, v29
	v_rcp_f32_e32 v14, v14
	v_rcp_f32_e32 v15, v15
	v_mul_f32_e32 v30, 0xbfb8aa3b, v30
	v_mul_f32_e32 v31, 0xbfb8aa3b, v31
	v_pk_mul_f32 v[28:29], v[34:35], v[8:9] op_sel_hi:[1,0]
	v_exp_f32_e32 v30, v30
	v_exp_f32_e32 v31, v31
	s_waitcnt lgkmcnt(0)
	v_pk_mul_f32 v[10:11], v[28:29], v[10:11]
	v_add_f32_e32 v28, 1.0, v30
	v_pk_mul_f32 v[10:11], v[10:11], v[14:15]
	v_pk_mul_f32 v[14:15], v[32:33], v[8:9] op_sel_hi:[1,0]
	v_cvt_pk_bf16_f32 v10, v10, v11
	v_add_u32_e32 v11, v141, v168
	v_add_f32_e32 v29, 1.0, v31
	v_pk_mul_f32 v[12:13], v[14:15], v[12:13]
	ds_read_b64 v[14:15], v11
	v_rcp_f32_e32 v28, v28
	v_rcp_f32_e32 v29, v29
	s_waitcnt lgkmcnt(0)
	v_and_b32_e32 v31, 0xffff0000, v15
	v_pk_mul_f32 v[12:13], v[12:13], v[28:29]
	v_lshlrev_b32_e32 v28, 16, v14
	v_and_b32_e32 v14, 0xffff0000, v14
	v_mul_f32_e32 v28, 0xbfb8aa3b, v28
	v_mul_f32_e32 v14, 0xbfb8aa3b, v14
	v_exp_f32_e32 v28, v28
	v_exp_f32_e32 v30, v14
	v_cvt_pk_bf16_f32 v11, v12, v13
	v_add_u32_e32 v12, v142, v167
	ds_write_b64 v12, v[10:11] offset:2048
	ds_read_b128 v[10:13], v9 offset:96
	v_lshlrev_b32_e32 v29, 16, v15
	v_add_f32_e32 v14, 1.0, v28
	v_add_f32_e32 v15, 1.0, v30
	v_rcp_f32_e32 v14, v14
	v_rcp_f32_e32 v15, v15
	v_mul_f32_e32 v28, 0xbfb8aa3b, v29
	v_mul_f32_e32 v29, 0xbfb8aa3b, v31
	s_waitcnt lgkmcnt(0)
	v_pk_mul_f32 v[10:11], v[26:27], v[10:11]
	v_exp_f32_e32 v28, v28
	v_exp_f32_e32 v29, v29
	v_pk_mul_f32 v[10:11], v[10:11], v[14:15]
	v_pk_mul_f32 v[14:15], v[24:25], v[8:9] op_sel_hi:[1,0]
	v_cvt_pk_bf16_f32 v10, v10, v11
	v_add_u32_e32 v11, v141, v169
	v_pk_mul_f32 v[12:13], v[14:15], v[12:13]
	ds_read_b64 v[14:15], v11
	v_add_f32_e32 v26, 1.0, v28
	v_add_f32_e32 v27, 1.0, v29
	v_rcp_f32_e32 v26, v26
	v_rcp_f32_e32 v27, v27
	s_waitcnt lgkmcnt(0)
	v_lshlrev_b32_e32 v24, 16, v14
	v_and_b32_e32 v14, 0xffff0000, v14
	v_mul_f32_e32 v24, 0xbfb8aa3b, v24
	v_mul_f32_e32 v14, 0xbfb8aa3b, v14
	v_pk_mul_f32 v[12:13], v[12:13], v[26:27]
	v_exp_f32_e32 v24, v24
	v_exp_f32_e32 v26, v14
	v_cvt_pk_bf16_f32 v11, v12, v13
	v_add_u32_e32 v12, v142, v168
	ds_write_b64 v12, v[10:11] offset:2048
	ds_read_b128 v[10:13], v9 offset:128
	v_lshlrev_b32_e32 v25, 16, v15
	v_and_b32_e32 v27, 0xffff0000, v15
	v_add_f32_e32 v14, 1.0, v24
	v_add_f32_e32 v15, 1.0, v26
	v_rcp_f32_e32 v14, v14
	v_rcp_f32_e32 v15, v15
	v_mul_f32_e32 v24, 0xbfb8aa3b, v25
	v_mul_f32_e32 v25, 0xbfb8aa3b, v27
	s_waitcnt lgkmcnt(0)
	v_pk_mul_f32 v[10:11], v[22:23], v[10:11]
	v_exp_f32_e32 v24, v24
	v_exp_f32_e32 v25, v25
	v_pk_mul_f32 v[10:11], v[10:11], v[14:15]
	v_pk_mul_f32 v[14:15], v[20:21], v[8:9] op_sel_hi:[1,0]
	v_cvt_pk_bf16_f32 v10, v10, v11
	v_add_u32_e32 v11, v141, v170
	v_pk_mul_f32 v[12:13], v[14:15], v[12:13]
	ds_read_b64 v[14:15], v11
	v_add_f32_e32 v22, 1.0, v24
	v_add_f32_e32 v23, 1.0, v25
	v_rcp_f32_e32 v22, v22
	v_rcp_f32_e32 v23, v23
	s_waitcnt lgkmcnt(0)
	v_lshlrev_b32_e32 v20, 16, v14
	v_and_b32_e32 v14, 0xffff0000, v14
	v_mul_f32_e32 v20, 0xbfb8aa3b, v20
	v_mul_f32_e32 v14, 0xbfb8aa3b, v14
	v_pk_mul_f32 v[12:13], v[12:13], v[22:23]
	v_exp_f32_e32 v20, v20
	v_exp_f32_e32 v22, v14
	v_cvt_pk_bf16_f32 v11, v12, v13
	v_add_u32_e32 v12, v142, v169
	ds_write_b64 v12, v[10:11] offset:2048
	ds_read_b128 v[10:13], v9 offset:160
	v_lshlrev_b32_e32 v21, 16, v15
	v_and_b32_e32 v23, 0xffff0000, v15
	v_add_f32_e32 v14, 1.0, v20
	v_add_f32_e32 v15, 1.0, v22
	v_rcp_f32_e32 v14, v14
	v_rcp_f32_e32 v15, v15
	s_waitcnt lgkmcnt(0)
	v_pk_mul_f32 v[10:11], v[18:19], v[10:11]
	v_mul_f32_e32 v20, 0xbfb8aa3b, v21
	v_mul_f32_e32 v21, 0xbfb8aa3b, v23
	v_pk_mul_f32 v[10:11], v[10:11], v[14:15]
	v_exp_f32_e32 v20, v20
	v_exp_f32_e32 v21, v21
	v_pk_mul_f32 v[14:15], v[16:17], v[8:9] op_sel_hi:[1,0]
	v_cvt_pk_bf16_f32 v10, v10, v11
	v_add_u32_e32 v11, v141, v171
	v_pk_mul_f32 v[12:13], v[14:15], v[12:13]
	ds_read_b64 v[14:15], v11
	v_add_f32_e32 v18, 1.0, v20
	v_add_f32_e32 v19, 1.0, v21
	v_rcp_f32_e32 v18, v18
	v_rcp_f32_e32 v19, v19
	s_waitcnt lgkmcnt(0)
	v_lshlrev_b32_e32 v16, 16, v14
	v_mul_f32_e32 v16, 0xbfb8aa3b, v16
	v_exp_f32_e32 v16, v16
	v_pk_mul_f32 v[12:13], v[12:13], v[18:19]
	v_and_b32_e32 v14, 0xffff0000, v14
	v_cvt_pk_bf16_f32 v11, v12, v13
	v_add_u32_e32 v12, v142, v170
	v_mul_f32_e32 v14, 0xbfb8aa3b, v14
	ds_write_b64 v12, v[10:11] offset:2048
	v_lshlrev_b32_e32 v17, 16, v15
	v_exp_f32_e32 v18, v14
	v_and_b32_e32 v19, 0xffff0000, v15
	ds_read_b128 v[10:13], v9 offset:192
	v_add_f32_e32 v14, 1.0, v16
	v_mul_f32_e32 v16, 0xbfb8aa3b, v17
	v_mul_f32_e32 v17, 0xbfb8aa3b, v19
	v_exp_f32_e32 v16, v16
	v_exp_f32_e32 v17, v17
	v_add_f32_e32 v15, 1.0, v18
	v_rcp_f32_e32 v14, v14
	v_rcp_f32_e32 v15, v15
	s_waitcnt lgkmcnt(0)
	v_pk_mul_f32 v[6:7], v[6:7], v[10:11]
	v_add_f32_e32 v10, 1.0, v16
	v_add_f32_e32 v11, 1.0, v17
	v_rcp_f32_e32 v10, v10
	v_rcp_f32_e32 v11, v11
	v_pk_mul_f32 v[6:7], v[6:7], v[14:15]
	v_pk_mul_f32 v[4:5], v[4:5], v[12:13]
	v_cvt_pk_bf16_f32 v6, v6, v7
	v_add_u32_e32 v7, v141, v172
	v_pk_mul_f32 v[4:5], v[4:5], v[10:11]
	ds_read_b64 v[10:11], v7
	v_cvt_pk_bf16_f32 v7, v4, v5
	v_add_u32_e32 v4, v142, v171
	ds_write_b64 v4, v[6:7] offset:2048
	ds_read_b128 v[4:7], v9 offset:224
	s_waitcnt lgkmcnt(2)
	v_lshlrev_b32_e32 v9, 16, v10
	v_and_b32_e32 v10, 0xffff0000, v10
	v_mul_f32_e32 v9, 0xbfb8aa3b, v9
	v_exp_f32_e32 v9, v9
	v_mul_f32_e32 v10, 0xbfb8aa3b, v10
	v_exp_f32_e32 v13, v10
	v_lshlrev_b32_e32 v12, 16, v11
	v_add_f32_e32 v9, 1.0, v9
	v_and_b32_e32 v14, 0xffff0000, v11
	v_rcp_f32_e32 v10, v9
	v_add_f32_e32 v9, 1.0, v13
	v_rcp_f32_e32 v11, v9
	v_pk_mul_f32 v[2:3], v[2:3], v[8:9] op_sel_hi:[1,0]
	v_mul_f32_e32 v9, 0xbfb8aa3b, v12
	v_mul_f32_e32 v12, 0xbfb8aa3b, v14
	v_exp_f32_e32 v9, v9
	v_exp_f32_e32 v12, v12
	s_waitcnt lgkmcnt(0)
	v_pk_mul_f32 v[2:3], v[2:3], v[4:5]
	v_add_f32_e32 v4, 1.0, v9
	v_add_f32_e32 v5, 1.0, v12
	v_rcp_f32_e32 v4, v4
	v_rcp_f32_e32 v5, v5
	v_pk_mul_f32 v[0:1], v[0:1], v[8:9] op_sel_hi:[1,0]
	v_pk_mul_f32 v[2:3], v[2:3], v[10:11]
	v_pk_mul_f32 v[0:1], v[0:1], v[6:7]
	v_cvt_pk_bf16_f32 v2, v2, v3
	v_pk_mul_f32 v[0:1], v[0:1], v[4:5]
	v_add_u32_e32 v4, s12, v150
	v_cvt_pk_bf16_f32 v3, v0, v1
	v_add_u32_e32 v0, v142, v172
	ds_write_b64 v0, v[2:3] offset:2048
	v_add_u32_e32 v0, v156, v143
	s_waitcnt lgkmcnt(0)
	s_waitcnt vmcnt(0)
	v_mov_b32_e32 v187, v186
	v_mov_b32_e32 v32, v129
	v_mov_b32_e32 v33, v185
	s_barrier
	ds_read_b128 v[0:3], v0 offset:2048
	v_ashrrev_i32_e32 v5, 31, v4
	v_lshl_add_u64 v[8:9], v[144:145], 0, s[68:69]
	v_lshlrev_b64 v[4:5], 11, v[4:5]
	v_lshl_add_u64 v[10:11], v[8:9], 0, v[4:5]
	v_add_u32_e32 v4, v156, v162
	ds_read_b128 v[4:7], v4 offset:2048
	s_waitcnt lgkmcnt(1)
	global_store_dwordx4 v[10:11], v[0:3], off
	s_nop 1
	v_add_u32_e32 v0, s12, v151
	v_ashrrev_i32_e32 v1, 31, v0
	v_lshlrev_b64 v[0:1], 11, v[0:1]
	v_lshl_add_u64 v[0:1], v[8:9], 0, v[0:1]
	s_waitcnt lgkmcnt(0)
	global_store_dwordx4 v[0:1], v[4:7], off
	v_add_u32_e32 v0, v156, v163
	ds_read_b128 v[0:3], v0 offset:2048
	v_add_u32_e32 v4, s12, v152
	v_ashrrev_i32_e32 v5, 31, v4
	v_lshlrev_b64 v[4:5], 11, v[4:5]
	v_lshl_add_u64 v[10:11], v[8:9], 0, v[4:5]
	v_add_u32_e32 v4, v156, v164
	ds_read_b128 v[4:7], v4 offset:2048
	s_waitcnt lgkmcnt(1)
	global_store_dwordx4 v[10:11], v[0:3], off
	s_nop 1
	v_add_u32_e32 v0, s12, v153
	v_ashrrev_i32_e32 v1, 31, v0
	v_lshlrev_b64 v[0:1], 11, v[0:1]
	v_lshl_add_u64 v[0:1], v[8:9], 0, v[0:1]
	s_waitcnt lgkmcnt(0)
	global_store_dwordx4 v[0:1], v[4:7], off
	s_cbranch_vccz .LBB0_628
